# nt policy also on the once-read xBC / v loads of the P2 layout pass
# speedup vs baseline: 1.0283x; 1.0111x over previous
; __device__ __forceinline__ void unpack8(u32x4 r, float* f) { f[0] = bflo(r.x); f[1] = bfhi(r.x); f[2] = bflo(r.y); f[3] = bfhi(r.y); f[4] = bflo(r.z); f[5] = bfhi(r.z); f[6] = bflo(r.w); f[7] = bfhi(r.w); }
; __device__ __forceinline__ void phase_layout(const PT& p, int tid) {
;     ...
;             const int sc0 = (k - 16) * 128 + co * 8;
;             float cw[4][8], cb[8];
; #pragma unroll
;             for (int j = 0; j < 8; ++j) { cb[j] = p.in[8][sc0 + j];
; #pragma unroll
;                 for (int kk = 0; kk < 4; ++kk) cw[kk][j] = p.in[7][kk * 3072 + sc0 + j]; }
;             const int pos0 = (bc & 15) * 128 + so * 8;
;             float xw[11][8];
; #pragma unroll
;             for (int ii = 0; ii < 11; ++ii) {
;                 if (pos0 - 3 + ii >= 0) unpack8(*(const u32x4*)(XBC + (size_t)(tok0 - 3 + ii) * 3072 + sc0), xw[ii]);
;                 else {
; #pragma unroll
;                     for (int j = 0; j < 8; ++j) xw[ii][j] = 0.f;
;                 }
;             }
.LBB0_262:
	v_mul_hi_i32 v0, v68, s25
	v_lshrrev_b32_e32 v1, 31, v0
	v_ashrrev_i32_e32 v0, 2, v0
	v_add_u32_e32 v82, v0, v1
	v_mad_u64_u32 v[88:89], s[0:1], v82, s27, v[68:69]
	v_lshlrev_b32_e32 v20, 7, v82
	v_or_b32_e32 v84, v20, v69
	v_cmp_lt_i32_e32 vcc, -1, v88
	s_and_saveexec_b64 s[0:1], vcc
	s_xor_b64 s[0:1], exec, s[0:1]
	s_cbranch_execz .LBB0_278
	ds_read_b64 v[0:1], v79
	ds_read_b64 v[4:5], v123
	v_mad_u64_u32 v[86:87], s[28:29], v82, s33, v[78:79]
	v_add_u32_e32 v70, 0xfffff7f9, v86
	s_waitcnt lgkmcnt(1)
	v_readfirstlane_b32 s29, v1
	v_readfirstlane_b32 s28, v0
	v_lshlrev_b64 v[6:7], 2, v[70:71]
	v_and_or_b32 v20, v20, s36, v69
	v_lshl_add_u64 v[8:9], s[28:29], 0, v[6:7]
	s_waitcnt lgkmcnt(0)
	v_readfirstlane_b32 s29, v5
	v_readfirstlane_b32 s28, v4
	global_load_dwordx4 v[0:3], v[8:9], off offset:16 nt
	global_load_dwordx4 v[48:51], v[8:9], off nt
	v_lshl_add_u64 v[8:9], s[28:29], 0, v[6:7]
	v_add_co_u32_e32 v6, vcc, s34, v8
	global_load_dwordx4 v[12:15], v[8:9], off offset:16 nt
	global_load_dwordx4 v[60:63], v[8:9], off nt
	v_addc_co_u32_e32 v7, vcc, 0, v9, vcc
	v_lshl_add_u64 v[4:5], v[8:9], 0, s[14:15]
	global_load_dwordx4 v[64:67], v[6:7], off nt
	global_load_dwordx4 v[16:19], v[4:5], off offset:16 nt
	v_add_co_u32_e32 v6, vcc, s35, v8
	v_lshl_add_u64 v[4:5], v[8:9], 0, s[16:17]
	s_nop 0
	v_addc_co_u32_e32 v7, vcc, 0, v9, vcc
	v_lshl_add_u64 v[10:11], v[8:9], 0, s[20:21]
	v_add_co_u32_e32 v8, vcc, 0x9000, v8
	global_load_dwordx4 v[52:55], v[6:7], off nt
	s_nop 0
	global_load_dwordx4 v[4:7], v[4:5], off offset:16 nt
	v_addc_co_u32_e32 v9, vcc, 0, v9, vcc
	global_load_dwordx4 v[56:59], v[8:9], off nt
	s_nop 0
	global_load_dwordx4 v[8:11], v[10:11], off offset:16 nt
	v_lshl_add_u64 v[28:29], v[70:71], 1, s[2:3]
	v_cmp_ne_u32_e32 vcc, 0, v20
	v_mov_b32_e32 v109, 0
	v_mov_b32_e32 v108, 0
	v_mov_b32_e32 v118, 0
	v_mov_b32_e32 v128, 0
	v_mov_b32_e32 v120, 0
	v_mov_b32_e32 v138, 0
	v_mov_b32_e32 v106, 0
	v_mov_b32_e32 v148, 0
	v_mov_b32_e32 v90, 0
	s_and_saveexec_b64 s[28:29], vcc
	s_cbranch_execz .LBB0_265
	v_add_u32_e32 v20, -3, v84
	v_mad_i64_i32 v[20:21], s[30:31], v20, s37, v[28:29]
	global_load_dwordx4 v[20:23], v[20:21], off nt
	s_waitcnt vmcnt(0)
	v_lshlrev_b32_e32 v90, 16, v20
	v_and_b32_e32 v148, 0xffff0000, v20
	v_lshlrev_b32_e32 v106, 16, v21
	v_and_b32_e32 v138, 0xffff0000, v21
	v_lshlrev_b32_e32 v120, 16, v22
	v_and_b32_e32 v128, 0xffff0000, v22
	v_lshlrev_b32_e32 v118, 16, v23
	v_and_b32_e32 v108, 0xffff0000, v23
.LBB0_265:
	s_or_b64 exec, exec, s[28:29]
	v_mov_b32_e32 v119, 0
	v_mov_b32_e32 v129, 0
	v_mov_b32_e32 v121, 0
	v_mov_b32_e32 v139, 0
	v_mov_b32_e32 v107, 0
	v_mov_b32_e32 v149, 0
	v_mov_b32_e32 v91, 0
	s_and_saveexec_b64 s[28:29], vcc
	s_cbranch_execz .LBB0_267
	v_add_u32_e32 v20, -2, v84
	v_mad_i64_i32 v[20:21], s[30:31], v20, s37, v[28:29]
	global_load_dwordx4 v[20:23], v[20:21], off nt
	s_waitcnt vmcnt(0)
	v_lshlrev_b32_e32 v91, 16, v20
	v_and_b32_e32 v149, 0xffff0000, v20
	v_lshlrev_b32_e32 v107, 16, v21
	v_and_b32_e32 v139, 0xffff0000, v21
	v_lshlrev_b32_e32 v121, 16, v22
	v_and_b32_e32 v129, 0xffff0000, v22
	v_lshlrev_b32_e32 v119, 16, v23
	v_and_b32_e32 v109, 0xffff0000, v23
.LBB0_267:
	s_or_b64 exec, exec, s[28:29]
	v_mov_b32_e32 v117, 0
	v_mov_b32_e32 v127, 0
	v_mov_b32_e32 v131, 0
	v_mov_b32_e32 v137, 0
	v_mov_b32_e32 v143, 0
	v_mov_b32_e32 v147, 0
	v_mov_b32_e32 v153, 0
	v_mov_b32_e32 v93, 0
	s_and_saveexec_b64 s[28:29], vcc
	s_cbranch_execz .LBB0_269
	v_add_u32_e32 v20, -1, v84
	v_mad_i64_i32 v[20:21], s[30:31], v20, s37, v[28:29]
	global_load_dwordx4 v[20:23], v[20:21], off nt
	s_waitcnt vmcnt(0)
	v_lshlrev_b32_e32 v93, 16, v20
	v_and_b32_e32 v153, 0xffff0000, v20
	v_lshlrev_b32_e32 v147, 16, v21
	v_and_b32_e32 v143, 0xffff0000, v21
	v_lshlrev_b32_e32 v137, 16, v22
	v_and_b32_e32 v131, 0xffff0000, v22
	v_lshlrev_b32_e32 v127, 16, v23
	v_and_b32_e32 v117, 0xffff0000, v23
.LBB0_269:
	s_or_b64 exec, exec, s[28:29]
	v_mad_i64_i32 v[20:21], s[28:29], v84, s37, v[28:29]
	v_or_b32_e32 v112, 2, v84
	v_or_b32_e32 v114, 3, v84
	v_or_b32_e32 v104, 4, v84
	v_or_b32_e32 v102, 5, v84
	global_load_dwordx4 v[94:97], v[20:21], off nt
	v_or_b32_e32 v110, 1, v84
	v_mad_i64_i32 v[20:21], s[28:29], v112, s37, v[28:29]
	v_mad_i64_i32 v[24:25], s[28:29], v114, s37, v[28:29]
	v_mad_i64_i32 v[30:31], s[28:29], v104, s37, v[28:29]
	v_mad_i64_i32 v[32:33], s[28:29], v102, s37, v[28:29]
	v_or_b32_e32 v100, 6, v84
	v_or_b32_e32 v98, 7, v84
	global_load_dwordx4 v[20:23], v[20:21], off nt
	s_nop 0
	global_load_dwordx4 v[24:27], v[24:25], off nt
	s_nop 0
	global_load_dwordx4 v[40:43], v[30:31], off nt
	s_nop 0
	global_load_dwordx4 v[32:35], v[32:33], off nt
	v_mad_i64_i32 v[30:31], s[28:29], v100, s37, v[28:29]
	v_mad_i64_i32 v[36:37], s[28:29], v98, s37, v[28:29]
	v_mad_i64_i32 v[28:29], s[28:29], v110, s37, v[28:29]
	global_load_dwordx4 v[44:47], v[30:31], off nt
	s_nop 0
	global_load_dwordx4 v[36:39], v[36:37], off nt
	v_mov_b32_e32 v92, v91
	global_load_dwordx4 v[28:31], v[28:29], off nt
	s_waitcnt vmcnt(14)
	v_pk_fma_f32 v[90:91], v[60:61], v[90:91], v[48:49] op_sel_hi:[0,1,0]
	v_mov_b32_e32 v156, v93
	s_waitcnt vmcnt(13)
	v_pk_fma_f32 v[90:91], v[64:65], v[92:93], v[90:91] op_sel_hi:[0,1,1]
	v_mov_b32_e32 v122, v15
	s_waitcnt vmcnt(12)
	v_mov_b32_e32 v124, v19
	v_mov_b32_e32 v132, v13
	v_mov_b32_e32 v134, v17
	v_mov_b32_e32 v152, v149
	v_pk_fma_f32 v[148:149], v[60:61], v[148:149], v[48:49] op_sel:[1,0,1]
	v_mov_b32_e32 v158, v153
	v_pk_fma_f32 v[148:149], v[64:65], v[152:153], v[148:149] op_sel:[1,0,0]
	v_mov_b32_e32 v146, v107
	v_pk_fma_f32 v[106:107], v[62:63], v[106:107], v[50:51] op_sel_hi:[0,1,0]
	v_pk_fma_f32 v[106:107], v[66:67], v[146:147], v[106:107] op_sel_hi:[0,1,1]
	v_mov_b32_e32 v160, v147
	v_mov_b32_e32 v140, v63
	v_mov_b32_e32 v144, v67
	v_mov_b32_e32 v142, v139
	v_mov_b32_e32 v150, v143
	v_mov_b32_e32 v136, v121
	v_mov_b32_e32 v130, v129
	v_mov_b32_e32 v126, v119
	v_mov_b32_e32 v116, v109
	v_cmp_lt_u32_e32 vcc, 15, v88
	s_waitcnt vmcnt(7)
; __device__ __forceinline__ float silu_f(float x) { return x * __builtin_amdgcn_rcpf(1.0f + __expf(-x)); }
; __device__ __forceinline__ void phase_layout(const PT& p, int tid) {
;     ...
; #pragma unroll
;             for (int i = 0; i < 8; ++i)
; #pragma unroll
;                 for (int j = 0; j < 8; ++j) { float a = cb[j];
; #pragma unroll
;                     for (int kk = 0; kk < 4; ++kk) a += cw[kk][j] * xw[i + kk][j];
;                     o[i][j] = silu_f(a); }
	v_lshlrev_b32_e32 v157, 16, v94
	v_pk_fma_f32 v[90:91], v[52:53], v[156:157], v[90:91] op_sel_hi:[0,1,1]
	v_mov_b32_e32 v166, v157
	v_pk_fma_f32 v[156:157], v[60:61], v[156:157], v[48:49] op_sel_hi:[0,1,0]
	v_and_b32_e32 v159, 0xffff0000, v94
	v_lshlrev_b32_e32 v161, 16, v95
	v_and_b32_e32 v151, 0xffff0000, v95
	v_lshlrev_b32_e32 v145, 16, v96
	v_and_b32_e32 v141, 0xffff0000, v96
	v_lshlrev_b32_e32 v17, 16, v97
	v_and_b32_e32 v13, 0xffff0000, v97
	s_waitcnt vmcnt(6)
	v_lshlrev_b32_e32 v165, 16, v20
	s_waitcnt vmcnt(4)
	v_lshlrev_b32_e32 v93, 16, v40
	v_lshlrev_b32_e32 v92, 16, v24
	s_waitcnt vmcnt(3)
	v_lshlrev_b32_e32 v95, 16, v32
	v_mov_b32_e32 v94, v93
	v_mov_b32_e32 v96, v95
	v_pk_fma_f32 v[148:149], v[52:53], v[158:159], v[148:149] op_sel:[1,0,0]
	v_mov_b32_e32 v152, v159
	s_waitcnt vmcnt(2)
	v_lshlrev_b32_e32 v97, 16, v44
	s_waitcnt vmcnt(1)
	v_lshlrev_b32_e32 v163, 16, v36
	v_mov_b32_e32 v162, v97
	s_waitcnt vmcnt(0)
	v_lshlrev_b32_e32 v164, 16, v28
	v_mov_b32_e32 v167, v164
	v_pk_fma_f32 v[156:157], v[64:65], v[166:167], v[156:157] op_sel_hi:[0,1,1]
	v_pk_mov_b32 v[170:171], v[164:165], v[92:93] op_sel:[1,0]
	v_pk_fma_f32 v[90:91], v[56:57], v[166:167], v[90:91] op_sel_hi:[0,1,1]
	v_pk_fma_f32 v[156:157], v[52:53], v[164:165], v[156:157] op_sel_hi:[0,1,1]
	v_mul_f32_e32 v15, 0xbfb8aa3b, v90
	v_pk_fma_f32 v[156:157], v[56:57], v[170:171], v[156:157] op_sel_hi:[0,1,1]
	v_exp_f32_e32 v15, v15
	v_mul_f32_e32 v81, 0xbfb8aa3b, v156
	v_exp_f32_e32 v81, v81
	v_pk_fma_f32 v[168:169], v[60:61], v[164:165], v[48:49] op_sel_hi:[0,1,0]
	v_pk_fma_f32 v[166:167], v[64:65], v[170:171], v[168:169] op_sel_hi:[0,1,1]
	v_mul_f32_e32 v19, 0xbfb8aa3b, v91
	v_pk_fma_f32 v[164:165], v[52:53], v[92:93], v[166:167] op_sel_hi:[0,1,1]
	v_add_f32_e32 v15, 1.0, v15
	v_exp_f32_e32 v19, v19
	v_pk_fma_f32 v[164:165], v[56:57], v[94:95], v[164:165] op_sel_hi:[0,1,1]
	v_mul_f32_e32 v83, 0xbfb8aa3b, v157
	v_rcp_f32_e32 v166, v15
	v_add_f32_e32 v15, 1.0, v81
	v_exp_f32_e32 v83, v83
	v_rcp_f32_e32 v168, v15
	v_mul_f32_e32 v15, 0xbfb8aa3b, v164
	v_exp_f32_e32 v15, v15
	v_mul_f32_e32 v81, 0xbfb8aa3b, v165
	v_pk_fma_f32 v[92:93], v[60:61], v[92:93], v[48:49] op_sel_hi:[0,1,0]
	v_exp_f32_e32 v81, v81
	v_pk_fma_f32 v[92:93], v[64:65], v[94:95], v[92:93] op_sel_hi:[0,1,1]
	v_add_f32_e32 v19, 1.0, v19
	v_pk_fma_f32 v[92:93], v[52:53], v[96:97], v[92:93] op_sel_hi:[0,1,1]
	v_rcp_f32_e32 v167, v19
	v_add_f32_e32 v19, 1.0, v83
	v_pk_fma_f32 v[96:97], v[56:57], v[162:163], v[92:93] op_sel_hi:[0,1,1]
	v_rcp_f32_e32 v169, v19
	v_add_f32_e32 v15, 1.0, v15
	v_mul_f32_e32 v19, 0xbfb8aa3b, v96
	v_rcp_f32_e32 v170, v15
	v_add_f32_e32 v15, 1.0, v81
	v_exp_f32_e32 v19, v19
	v_mul_f32_e32 v81, 0xbfb8aa3b, v97
	v_exp_f32_e32 v81, v81
	v_pk_mul_f32 v[92:93], v[156:157], v[168:169]
	v_and_b32_e32 v168, 0xffff0000, v28
	v_rcp_f32_e32 v171, v15
	v_add_f32_e32 v15, 1.0, v19
	v_mov_b32_e32 v153, v168
	v_rcp_f32_e32 v162, v15
	v_add_f32_e32 v15, 1.0, v81
	v_pk_fma_f32 v[148:149], v[56:57], v[152:153], v[148:149] op_sel:[1,0,0]
	v_rcp_f32_e32 v163, v15
	v_mul_f32_e32 v15, 0xbfb8aa3b, v148
	v_exp_f32_e32 v15, v15
	v_mul_f32_e32 v19, 0xbfb8aa3b, v149
	v_exp_f32_e32 v19, v19
	v_pk_fma_f32 v[158:159], v[60:61], v[158:159], v[48:49] op_sel:[1,0,1]
	v_and_b32_e32 v157, 0xffff0000, v40
	v_and_b32_e32 v156, 0xffff0000, v24
	v_and_b32_e32 v169, 0xffff0000, v20
	v_pk_fma_f32 v[152:153], v[64:65], v[152:153], v[158:159] op_sel:[1,0,0]
	v_add_f32_e32 v15, 1.0, v15
	v_pk_mov_b32 v[172:173], v[168:169], v[156:157] op_sel:[1,0]
	v_pk_fma_f32 v[152:153], v[52:53], v[168:169], v[152:153] op_sel:[1,0,0]
	v_pk_mul_f32 v[94:95], v[164:165], v[170:171]
	v_rcp_f32_e32 v170, v15
	v_add_f32_e32 v15, 1.0, v19
	v_pk_fma_f32 v[152:153], v[56:57], v[172:173], v[152:153] op_sel:[1,0,0]
	v_rcp_f32_e32 v171, v15
	v_mul_f32_e32 v15, 0xbfb8aa3b, v152
	v_exp_f32_e32 v15, v15
	v_mul_f32_e32 v19, 0xbfb8aa3b, v153
	v_exp_f32_e32 v19, v19
	v_pk_fma_f32 v[158:159], v[60:61], v[168:169], v[48:49] op_sel:[1,0,1]
	v_pk_mul_f32 v[96:97], v[96:97], v[162:163]
	v_pk_fma_f32 v[158:159], v[64:65], v[172:173], v[158:159] op_sel:[1,0,0]
	v_and_b32_e32 v163, 0xffff0000, v32
	v_mov_b32_e32 v162, v157
	v_pk_fma_f32 v[158:159], v[52:53], v[156:157], v[158:159] op_sel:[1,0,0]
	v_add_f32_e32 v15, 1.0, v15
	v_pk_fma_f32 v[158:159], v[56:57], v[162:163], v[158:159] op_sel:[1,0,0]
	v_rcp_f32_e32 v168, v15
	v_add_f32_e32 v15, 1.0, v19
	v_mul_f32_e32 v19, 0xbfb8aa3b, v158
	v_exp_f32_e32 v19, v19
	v_mul_f32_e32 v20, 0xbfb8aa3b, v159
	v_exp_f32_e32 v20, v20
	v_pk_fma_f32 v[48:49], v[60:61], v[156:157], v[48:49] op_sel:[1,0,1]
	v_and_b32_e32 v165, 0xffff0000, v44
	v_mov_b32_e32 v164, v163
	v_pk_fma_f32 v[48:49], v[64:65], v[162:163], v[48:49] op_sel:[1,0,0]
	v_pk_mul_f32 v[90:91], v[90:91], v[166:167]
	v_and_b32_e32 v167, 0xffff0000, v36
	v_mov_b32_e32 v166, v165
	v_rcp_f32_e32 v169, v15
	v_add_f32_e32 v15, 1.0, v19
	v_pk_fma_f32 v[48:49], v[52:53], v[164:165], v[48:49] op_sel:[1,0,0]
	v_rcp_f32_e32 v172, v15
	v_add_f32_e32 v15, 1.0, v20
	v_pk_fma_f32 v[60:61], v[56:57], v[166:167], v[48:49] op_sel:[1,0,0]
	v_rcp_f32_e32 v173, v15
	v_mul_f32_e32 v19, 0xbfb8aa3b, v60
	v_exp_f32_e32 v19, v19
	v_mul_f32_e32 v20, 0xbfb8aa3b, v61
	v_exp_f32_e32 v20, v20
	v_pk_mul_f32 v[56:57], v[158:159], v[172:173]
	v_lshlrev_b32_e32 v158, 16, v29
	v_add_f32_e32 v15, 1.0, v19
	v_pk_fma_f32 v[106:107], v[54:55], v[160:161], v[106:107] op_sel_hi:[0,1,1]
	v_mov_b32_e32 v146, v161
	v_mov_b32_e32 v147, v158
	v_rcp_f32_e32 v64, v15
	v_add_f32_e32 v15, 1.0, v20
	v_pk_fma_f32 v[106:107], v[58:59], v[146:147], v[106:107] op_sel_hi:[0,1,1]
	v_rcp_f32_e32 v65, v15
	v_mul_f32_e32 v15, 0xbfb8aa3b, v106
; __device__ __forceinline__ float silu_f(float x) { return x * __builtin_amdgcn_rcpf(1.0f + __expf(-x)); }
; __device__ __forceinline__ void phase_layout(const PT& p, int tid) {
;     ...
; #pragma unroll
;             for (int i = 0; i < 8; ++i)
; #pragma unroll
;                 for (int j = 0; j < 8; ++j) { float a = cb[j];
; #pragma unroll
;                     for (int kk = 0; kk < 4; ++kk) a += cw[kk][j] * xw[i + kk][j];
;                     o[i][j] = silu_f(a); }
	v_exp_f32_e32 v15, v15
	v_mul_f32_e32 v19, 0xbfb8aa3b, v107
	v_exp_f32_e32 v19, v19
	v_pk_fma_f32 v[160:161], v[62:63], v[160:161], v[50:51] op_sel_hi:[0,1,0]
	v_pk_mul_f32 v[60:61], v[60:61], v[64:65]
	v_lshlrev_b32_e32 v65, 16, v41
	v_lshlrev_b32_e32 v64, 16, v25
	v_lshlrev_b32_e32 v159, 16, v21
	v_pk_fma_f32 v[146:147], v[66:67], v[146:147], v[160:161] op_sel_hi:[0,1,1]
	v_add_f32_e32 v15, 1.0, v15
	v_pk_mov_b32 v[164:165], v[158:159], v[64:65] op_sel:[1,0]
	v_pk_fma_f32 v[146:147], v[54:55], v[158:159], v[146:147] op_sel_hi:[0,1,1]
	v_rcp_f32_e32 v162, v15
	v_add_f32_e32 v15, 1.0, v19
	v_pk_fma_f32 v[146:147], v[58:59], v[164:165], v[146:147] op_sel_hi:[0,1,1]
	v_rcp_f32_e32 v163, v15
	v_mul_f32_e32 v15, 0xbfb8aa3b, v146
	v_exp_f32_e32 v15, v15
	v_mul_f32_e32 v19, 0xbfb8aa3b, v147
	v_exp_f32_e32 v19, v19
	v_pk_fma_f32 v[158:159], v[62:63], v[158:159], v[50:51] op_sel_hi:[0,1,0]
	v_pk_fma_f32 v[158:159], v[66:67], v[164:165], v[158:159] op_sel_hi:[0,1,1]
	v_pk_mul_f32 v[48:49], v[148:149], v[170:171]
	v_lshlrev_b32_e32 v149, 16, v33
	v_mov_b32_e32 v148, v65
	v_pk_fma_f32 v[158:159], v[54:55], v[64:65], v[158:159] op_sel_hi:[0,1,1]
	v_add_f32_e32 v15, 1.0, v15
	v_pk_fma_f32 v[158:159], v[58:59], v[148:149], v[158:159] op_sel_hi:[0,1,1]
	v_rcp_f32_e32 v160, v15
	v_add_f32_e32 v15, 1.0, v19
	v_mul_f32_e32 v19, 0xbfb8aa3b, v158
	v_exp_f32_e32 v19, v19
	v_mul_f32_e32 v20, 0xbfb8aa3b, v159
	v_pk_fma_f32 v[62:63], v[62:63], v[64:65], v[50:51] op_sel_hi:[0,1,0]
	v_pk_mul_f32 v[52:53], v[152:153], v[168:169]
	v_lshlrev_b32_e32 v153, 16, v45
	v_mov_b32_e32 v152, v149
	v_exp_f32_e32 v20, v20
	v_pk_fma_f32 v[62:63], v[66:67], v[148:149], v[62:63] op_sel_hi:[0,1,1]
	v_lshlrev_b32_e32 v157, 16, v37
	v_mov_b32_e32 v156, v153
	v_pk_fma_f32 v[62:63], v[54:55], v[152:153], v[62:63] op_sel_hi:[0,1,1]
	v_pk_fma_f32 v[148:149], v[58:59], v[156:157], v[62:63] op_sel_hi:[0,1,1]
	v_rcp_f32_e32 v161, v15
	v_add_f32_e32 v15, 1.0, v19
	v_mul_f32_e32 v19, 0xbfb8aa3b, v148
	v_rcp_f32_e32 v164, v15
	v_add_f32_e32 v15, 1.0, v20
	v_exp_f32_e32 v19, v19
	v_mul_f32_e32 v20, 0xbfb8aa3b, v149
	v_exp_f32_e32 v20, v20
	v_mov_b32_e32 v28, v51
	v_rcp_f32_e32 v165, v15
	v_add_f32_e32 v15, 1.0, v19
	v_and_b32_e32 v40, 0xffff0000, v25
	v_and_b32_e32 v25, 0xffff0000, v33
	v_and_b32_e32 v33, 0xffff0000, v45
	v_pk_fma_f32 v[44:45], v[140:141], v[138:139], v[28:29] op_sel_hi:[0,1,0]
	v_rcp_f32_e32 v152, v15
	v_add_f32_e32 v15, 1.0, v20
	v_and_b32_e32 v20, 0xffff0000, v29
	v_pk_fma_f32 v[44:45], v[144:145], v[142:143], v[44:45] op_sel_hi:[0,1,1]
	v_mov_b32_e32 v50, v55
	v_pk_fma_f32 v[44:45], v[50:51], v[150:151], v[44:45] op_sel_hi:[0,1,1]
	v_mov_b32_e32 v54, v59
	v_mov_b32_e32 v58, v151
	v_mov_b32_e32 v59, v20
	v_pk_fma_f32 v[44:45], v[54:55], v[58:59], v[44:45] op_sel_hi:[0,1,1]
	v_rcp_f32_e32 v153, v15
	v_mul_f32_e32 v15, 0xbfb8aa3b, v44
	v_exp_f32_e32 v15, v15
	v_mul_f32_e32 v19, 0xbfb8aa3b, v45
	v_exp_f32_e32 v19, v19
	v_pk_fma_f32 v[142:143], v[140:141], v[150:151], v[28:29] op_sel_hi:[0,1,0]
	v_and_b32_e32 v41, 0xffff0000, v41
	v_and_b32_e32 v21, 0xffff0000, v21
	v_pk_fma_f32 v[58:59], v[144:145], v[58:59], v[142:143] op_sel_hi:[0,1,1]
	v_pk_mul_f32 v[64:65], v[146:147], v[160:161]
	v_add_f32_e32 v15, 1.0, v15
	v_pk_mov_b32 v[146:147], v[20:21], v[40:41] op_sel:[1,0]
	v_pk_fma_f32 v[58:59], v[50:51], v[20:21], v[58:59] op_sel_hi:[0,1,1]
	v_rcp_f32_e32 v138, v15
	v_add_f32_e32 v15, 1.0, v19
	v_pk_fma_f32 v[58:59], v[54:55], v[146:147], v[58:59] op_sel_hi:[0,1,1]
	v_rcp_f32_e32 v139, v15
	v_mul_f32_e32 v15, 0xbfb8aa3b, v58
	v_exp_f32_e32 v15, v15
	v_mul_f32_e32 v19, 0xbfb8aa3b, v59
	v_exp_f32_e32 v19, v19
	v_pk_fma_f32 v[20:21], v[140:141], v[20:21], v[28:29] op_sel_hi:[0,1,0]
	v_pk_fma_f32 v[20:21], v[144:145], v[146:147], v[20:21] op_sel_hi:[0,1,1]
	v_mov_b32_e32 v24, v41
	v_pk_fma_f32 v[20:21], v[50:51], v[40:41], v[20:21] op_sel_hi:[0,1,1]
	v_add_f32_e32 v15, 1.0, v15
	v_pk_fma_f32 v[20:21], v[54:55], v[24:25], v[20:21] op_sel_hi:[0,1,1]
	v_rcp_f32_e32 v142, v15
	v_add_f32_e32 v15, 1.0, v19
	v_mul_f32_e32 v19, 0xbfb8aa3b, v20
	v_exp_f32_e32 v19, v19
	v_mul_f32_e32 v29, 0xbfb8aa3b, v21
	v_exp_f32_e32 v29, v29
	v_rcp_f32_e32 v143, v15
	v_add_f32_e32 v15, 1.0, v19
	v_rcp_f32_e32 v146, v15
	v_add_f32_e32 v15, 1.0, v29
	v_pk_fma_f32 v[28:29], v[140:141], v[40:41], v[28:29] op_sel_hi:[0,1,0]
	v_mov_b32_e32 v32, v25
	v_pk_fma_f32 v[24:25], v[144:145], v[24:25], v[28:29] op_sel_hi:[0,1,1]
	v_and_b32_e32 v37, 0xffff0000, v37
	v_mov_b32_e32 v36, v33
	v_pk_fma_f32 v[24:25], v[50:51], v[32:33], v[24:25] op_sel_hi:[0,1,1]
	v_pk_fma_f32 v[24:25], v[54:55], v[36:37], v[24:25] op_sel_hi:[0,1,1]
	v_mul_f32_e32 v19, 0xbfb8aa3b, v24
	v_exp_f32_e32 v19, v19
	v_mul_f32_e32 v28, 0xbfb8aa3b, v25
	v_exp_f32_e32 v29, v28
	v_rcp_f32_e32 v147, v15
	v_add_f32_e32 v15, 1.0, v19
	v_pk_mul_f32 v[36:37], v[58:59], v[142:143]
	v_pk_fma_f32 v[58:59], v[12:13], v[120:121], v[0:1] op_sel_hi:[0,1,0]
	v_rcp_f32_e32 v28, v15
	v_add_f32_e32 v15, 1.0, v29
	v_lshlrev_b32_e32 v54, 16, v30
	v_pk_fma_f32 v[58:59], v[16:17], v[136:137], v[58:59] op_sel_hi:[0,1,1]
	v_mov_b32_e32 v144, v137
	v_rcp_f32_e32 v29, v15
	v_pk_mul_f32 v[32:33], v[44:45], v[138:139]
	v_pk_fma_f32 v[58:59], v[4:5], v[144:145], v[58:59] op_sel_hi:[0,1,1]
	v_mov_b32_e32 v120, v145
	v_mov_b32_e32 v121, v54
	v_pk_fma_f32 v[138:139], v[12:13], v[144:145], v[0:1] op_sel_hi:[0,1,0]
	v_pk_mul_f32 v[40:41], v[20:21], v[146:147]
	v_lshlrev_b32_e32 v21, 16, v42
	v_lshlrev_b32_e32 v20, 16, v26
	v_pk_fma_f32 v[58:59], v[8:9], v[120:121], v[58:59] op_sel_hi:[0,1,1]
	v_lshlrev_b32_e32 v55, 16, v22
	v_pk_fma_f32 v[120:121], v[16:17], v[120:121], v[138:139] op_sel_hi:[0,1,1]
; __device__ __forceinline__ float silu_f(float x) { return x * __builtin_amdgcn_rcpf(1.0f + __expf(-x)); }
; __device__ __forceinline__ void phase_layout(const PT& p, int tid) {
;     ...
; #pragma unroll
;             for (int i = 0; i < 8; ++i)
; #pragma unroll
;                 for (int j = 0; j < 8; ++j) { float a = cb[j];
; #pragma unroll
;                     for (int kk = 0; kk < 4; ++kk) a += cw[kk][j] * xw[i + kk][j];
;                     o[i][j] = silu_f(a); }
	v_pk_mov_b32 v[142:143], v[54:55], v[20:21] op_sel:[1,0]
	v_pk_fma_f32 v[120:121], v[4:5], v[54:55], v[120:121] op_sel_hi:[0,1,1]
	v_pk_fma_f32 v[54:55], v[12:13], v[54:55], v[0:1] op_sel_hi:[0,1,0]
	v_pk_fma_f32 v[54:55], v[16:17], v[142:143], v[54:55] op_sel_hi:[0,1,1]
	v_pk_mul_f32 v[44:45], v[24:25], v[28:29]
	v_lshlrev_b32_e32 v25, 16, v34
	v_mov_b32_e32 v24, v21
	v_mul_f32_e32 v15, 0xbfb8aa3b, v58
	v_pk_fma_f32 v[54:55], v[4:5], v[20:21], v[54:55] op_sel_hi:[0,1,1]
	v_pk_fma_f32 v[20:21], v[12:13], v[20:21], v[0:1] op_sel_hi:[0,1,0]
	v_lshlrev_b32_e32 v29, 16, v46
	v_mov_b32_e32 v28, v25
	v_exp_f32_e32 v15, v15
	v_mul_f32_e32 v19, 0xbfb8aa3b, v59
	v_pk_fma_f32 v[20:21], v[16:17], v[24:25], v[20:21] op_sel_hi:[0,1,1]
	v_lshlrev_b32_e32 v51, 16, v38
	v_mov_b32_e32 v50, v29
	v_exp_f32_e32 v19, v19
	v_pk_fma_f32 v[20:21], v[4:5], v[28:29], v[20:21] op_sel_hi:[0,1,1]
	v_pk_fma_f32 v[20:21], v[8:9], v[50:51], v[20:21] op_sel_hi:[0,1,1]
	v_mul_f32_e32 v0, 0xbfb8aa3b, v20
	v_add_f32_e32 v15, 1.0, v15
	v_exp_f32_e32 v0, v0
	v_mul_f32_e32 v4, 0xbfb8aa3b, v21
	v_rcp_f32_e32 v136, v15
	v_add_f32_e32 v15, 1.0, v19
	v_pk_fma_f32 v[120:121], v[8:9], v[142:143], v[120:121] op_sel_hi:[0,1,1]
	v_exp_f32_e32 v4, v4
	v_rcp_f32_e32 v137, v15
	v_mul_f32_e32 v15, 0xbfb8aa3b, v120
	v_exp_f32_e32 v15, v15
	v_mul_f32_e32 v19, 0xbfb8aa3b, v121
	v_exp_f32_e32 v19, v19
	v_add_f32_e32 v0, 1.0, v0
	v_pk_fma_f32 v[142:143], v[8:9], v[24:25], v[54:55] op_sel_hi:[0,1,1]
	v_rcp_f32_e32 v24, v0
	v_add_f32_e32 v0, 1.0, v4
	v_mov_b32_e32 v4, v1
	v_pk_fma_f32 v[128:129], v[132:133], v[128:129], v[4:5] op_sel_hi:[0,1,0]
	v_add_f32_e32 v15, 1.0, v15
	v_rcp_f32_e32 v25, v0
	v_and_b32_e32 v0, 0xffff0000, v30
	v_pk_fma_f32 v[128:129], v[134:135], v[130:131], v[128:129] op_sel_hi:[0,1,1]
	v_mov_b32_e32 v8, v5
	v_mov_b32_e32 v140, v131
	v_rcp_f32_e32 v138, v15
	v_add_f32_e32 v15, 1.0, v19
	v_mul_f32_e32 v19, 0xbfb8aa3b, v142
	v_pk_fma_f32 v[128:129], v[8:9], v[140:141], v[128:129] op_sel_hi:[0,1,1]
	v_mov_b32_e32 v12, v9
	v_mov_b32_e32 v130, v141
	v_mov_b32_e32 v131, v0
	v_exp_f32_e32 v19, v19
	v_mul_f32_e32 v54, 0xbfb8aa3b, v143
	v_pk_fma_f32 v[128:129], v[12:13], v[130:131], v[128:129] op_sel_hi:[0,1,1]
	v_exp_f32_e32 v54, v54
	v_mul_f32_e32 v1, 0xbfb8aa3b, v128
	v_exp_f32_e32 v5, v1
	v_mul_f32_e32 v1, 0xbfb8aa3b, v129
	v_rcp_f32_e32 v139, v15
	v_exp_f32_e32 v9, v1
	v_add_f32_e32 v15, 1.0, v19
	v_rcp_f32_e32 v144, v15
	v_add_f32_e32 v15, 1.0, v54
	v_rcp_f32_e32 v145, v15
	v_add_f32_e32 v5, 1.0, v5
	v_pk_mul_f32 v[54:55], v[120:121], v[138:139]
	v_rcp_f32_e32 v138, v5
	v_add_f32_e32 v5, 1.0, v9
	v_pk_fma_f32 v[140:141], v[132:133], v[140:141], v[4:5] op_sel_hi:[0,1,0]
	v_pk_mul_f32 v[120:121], v[20:21], v[24:25]
	v_and_b32_e32 v21, 0xffff0000, v42
	v_and_b32_e32 v20, 0xffff0000, v26
	v_and_b32_e32 v1, 0xffff0000, v22
	v_pk_fma_f32 v[130:131], v[134:135], v[130:131], v[140:141] op_sel_hi:[0,1,1]
	v_pk_mul_f32 v[50:51], v[58:59], v[136:137]
	v_pk_mul_f32 v[58:59], v[142:143], v[144:145]
	v_pk_mov_b32 v[142:143], v[0:1], v[20:21] op_sel:[1,0]
	v_pk_fma_f32 v[130:131], v[8:9], v[0:1], v[130:131] op_sel_hi:[0,1,1]
	v_pk_fma_f32 v[130:131], v[12:13], v[142:143], v[130:131] op_sel_hi:[0,1,1]
	v_rcp_f32_e32 v139, v5
	v_mul_f32_e32 v5, 0xbfb8aa3b, v130
	v_exp_f32_e32 v5, v5
	v_mul_f32_e32 v9, 0xbfb8aa3b, v131
	v_exp_f32_e32 v9, v9
	v_and_b32_e32 v25, 0xffff0000, v34
	v_pk_fma_f32 v[0:1], v[132:133], v[0:1], v[4:5] op_sel_hi:[0,1,0]
	v_pk_fma_f32 v[0:1], v[134:135], v[142:143], v[0:1] op_sel_hi:[0,1,1]
	v_mov_b32_e32 v24, v21
	v_pk_fma_f32 v[0:1], v[8:9], v[20:21], v[0:1] op_sel_hi:[0,1,1]
	v_add_f32_e32 v5, 1.0, v5
	v_pk_fma_f32 v[0:1], v[12:13], v[24:25], v[0:1] op_sel_hi:[0,1,1]
	v_rcp_f32_e32 v140, v5
	v_add_f32_e32 v5, 1.0, v9
	v_mul_f32_e32 v9, 0xbfb8aa3b, v0
	v_exp_f32_e32 v9, v9
	v_mul_f32_e32 v15, 0xbfb8aa3b, v1
	v_exp_f32_e32 v15, v15
	v_rcp_f32_e32 v141, v5
	v_add_f32_e32 v5, 1.0, v9
	v_rcp_f32_e32 v142, v5
	v_pk_fma_f32 v[4:5], v[132:133], v[20:21], v[4:5] op_sel_hi:[0,1,0]
	v_and_b32_e32 v29, 0xffff0000, v46
	v_mov_b32_e32 v28, v25
	v_add_f32_e32 v9, 1.0, v15
	v_pk_fma_f32 v[4:5], v[134:135], v[24:25], v[4:5] op_sel_hi:[0,1,1]
	v_and_b32_e32 v137, 0xffff0000, v38
	v_mov_b32_e32 v136, v29
	v_pk_fma_f32 v[4:5], v[8:9], v[28:29], v[4:5] op_sel_hi:[0,1,1]
	v_pk_fma_f32 v[28:29], v[14:15], v[118:119], v[2:3] op_sel_hi:[0,1,0]
	v_pk_fma_f32 v[4:5], v[12:13], v[136:137], v[4:5] op_sel_hi:[0,1,1]
	v_lshlrev_b32_e32 v24, 16, v31
	v_pk_fma_f32 v[28:29], v[18:19], v[126:127], v[28:29] op_sel_hi:[0,1,1]
	v_mov_b32_e32 v16, v127
	v_mul_f32_e32 v12, 0xbfb8aa3b, v5
	v_pk_fma_f32 v[28:29], v[6:7], v[16:17], v[28:29] op_sel_hi:[0,1,1]
	v_mov_b32_e32 v118, v17
	v_mov_b32_e32 v119, v24
	v_exp_f32_e32 v12, v12
	v_pk_fma_f32 v[28:29], v[10:11], v[118:119], v[28:29] op_sel_hi:[0,1,1]
	v_mul_f32_e32 v15, 0xbfb8aa3b, v29
	v_exp_f32_e32 v15, v15
	v_rcp_f32_e32 v143, v9
	v_add_f32_e32 v9, 1.0, v12
	v_mul_f32_e32 v12, 0xbfb8aa3b, v28
	v_exp_f32_e32 v12, v12
	v_pk_fma_f32 v[16:17], v[14:15], v[16:17], v[2:3] op_sel_hi:[0,1,0]
	v_mul_f32_e32 v8, 0xbfb8aa3b, v4
	v_pk_mul_f32 v[132:133], v[0:1], v[142:143]
	v_lshlrev_b32_e32 v1, 16, v43
	v_lshlrev_b32_e32 v0, 16, v27
	v_lshlrev_b32_e32 v25, 16, v23
	v_pk_fma_f32 v[16:17], v[18:19], v[118:119], v[16:17] op_sel_hi:[0,1,1]
	v_exp_f32_e32 v8, v8
	v_pk_mov_b32 v[136:137], v[24:25], v[0:1] op_sel:[1,0]
	v_pk_fma_f32 v[16:17], v[6:7], v[24:25], v[16:17] op_sel_hi:[0,1,1]
	v_add_f32_e32 v12, 1.0, v12
	v_pk_fma_f32 v[16:17], v[10:11], v[136:137], v[16:17] op_sel_hi:[0,1,1]
	v_rcp_f32_e32 v126, v12
	v_add_f32_e32 v12, 1.0, v15
	v_mul_f32_e32 v15, 0xbfb8aa3b, v17
; __device__ __forceinline__ float silu_f(float x) { return x * __builtin_amdgcn_rcpf(1.0f + __expf(-x)); }
; __device__ __forceinline__ void phase_layout(const PT& p, int tid) {
;     ...
; #pragma unroll
;             for (int i = 0; i < 8; ++i)
; #pragma unroll
;                 for (int j = 0; j < 8; ++j) { float a = cb[j];
; #pragma unroll
;                     for (int kk = 0; kk < 4; ++kk) a += cw[kk][j] * xw[i + kk][j];
;                     o[i][j] = silu_f(a); }
;             if (k < 32) {
	v_exp_f32_e32 v15, v15
	v_add_f32_e32 v8, 1.0, v8
	v_rcp_f32_e32 v8, v8
	v_rcp_f32_e32 v9, v9
	v_rcp_f32_e32 v127, v12
	v_mul_f32_e32 v12, 0xbfb8aa3b, v16
	v_exp_f32_e32 v12, v12
	v_pk_fma_f32 v[24:25], v[14:15], v[24:25], v[2:3] op_sel_hi:[0,1,0]
	v_pk_fma_f32 v[24:25], v[18:19], v[136:137], v[24:25] op_sel_hi:[0,1,1]
	v_pk_mul_f32 v[134:135], v[4:5], v[8:9]
	v_lshlrev_b32_e32 v5, 16, v35
	v_mov_b32_e32 v4, v1
	v_pk_fma_f32 v[24:25], v[6:7], v[0:1], v[24:25] op_sel_hi:[0,1,1]
	v_add_f32_e32 v12, 1.0, v12
	v_pk_fma_f32 v[24:25], v[10:11], v[4:5], v[24:25] op_sel_hi:[0,1,1]
	v_pk_mul_f32 v[128:129], v[128:129], v[138:139]
	v_rcp_f32_e32 v138, v12
	v_add_f32_e32 v12, 1.0, v15
	v_mul_f32_e32 v15, 0xbfb8aa3b, v24
	v_exp_f32_e32 v15, v15
	v_mul_f32_e32 v19, 0xbfb8aa3b, v25
	v_exp_f32_e32 v19, v19
	v_lshlrev_b32_e32 v9, 16, v47
	v_pk_fma_f32 v[0:1], v[14:15], v[0:1], v[2:3] op_sel_hi:[0,1,0]
	v_mov_b32_e32 v8, v5
	v_pk_fma_f32 v[0:1], v[18:19], v[4:5], v[0:1] op_sel_hi:[0,1,1]
	v_lshlrev_b32_e32 v21, 16, v39
	v_mov_b32_e32 v20, v9
	v_pk_fma_f32 v[0:1], v[6:7], v[8:9], v[0:1] op_sel_hi:[0,1,1]
	v_pk_fma_f32 v[0:1], v[10:11], v[20:21], v[0:1] op_sel_hi:[0,1,1]
	v_mul_f32_e32 v2, 0xbfb8aa3b, v0
	v_exp_f32_e32 v2, v2
	v_mul_f32_e32 v4, 0xbfb8aa3b, v1
	v_rcp_f32_e32 v139, v12
	v_exp_f32_e32 v5, v4
	v_add_f32_e32 v12, 1.0, v15
	v_add_f32_e32 v2, 1.0, v2
	v_mov_b32_e32 v6, v3
	v_rcp_f32_e32 v136, v12
	v_add_f32_e32 v12, 1.0, v19
	v_rcp_f32_e32 v4, v2
	v_add_f32_e32 v2, 1.0, v5
	v_pk_mul_f32 v[118:119], v[28:29], v[126:127]
	v_pk_mul_f32 v[126:127], v[16:17], v[138:139]
	v_pk_fma_f32 v[16:17], v[122:123], v[108:109], v[6:7] op_sel_hi:[0,1,0]
	v_rcp_f32_e32 v137, v12
	v_rcp_f32_e32 v5, v2
	v_and_b32_e32 v2, 0xffff0000, v31
	v_pk_fma_f32 v[16:17], v[124:125], v[116:117], v[16:17] op_sel_hi:[0,1,1]
	v_mov_b32_e32 v10, v7
	v_mov_b32_e32 v12, v117
	v_pk_fma_f32 v[16:17], v[10:11], v[12:13], v[16:17] op_sel_hi:[0,1,1]
	v_mov_b32_e32 v18, v11
	v_mov_b32_e32 v20, v13
	v_mov_b32_e32 v21, v2
	v_pk_fma_f32 v[16:17], v[18:19], v[20:21], v[16:17] op_sel_hi:[0,1,1]
	v_mul_f32_e32 v3, 0xbfb8aa3b, v16
	v_exp_f32_e32 v7, v3
	v_mul_f32_e32 v3, 0xbfb8aa3b, v17
	v_exp_f32_e32 v11, v3
	v_pk_mul_f32 v[138:139], v[0:1], v[4:5]
	v_add_f32_e32 v7, 1.0, v7
	v_rcp_f32_e32 v22, v7
	v_add_f32_e32 v7, 1.0, v11
	v_pk_fma_f32 v[12:13], v[122:123], v[12:13], v[6:7] op_sel_hi:[0,1,0]
	v_and_b32_e32 v1, 0xffff0000, v43
	v_and_b32_e32 v0, 0xffff0000, v27
	v_and_b32_e32 v3, 0xffff0000, v23
	v_pk_fma_f32 v[12:13], v[124:125], v[20:21], v[12:13] op_sel_hi:[0,1,1]
	v_pk_mul_f32 v[136:137], v[24:25], v[136:137]
	v_pk_mov_b32 v[24:25], v[2:3], v[0:1] op_sel:[1,0]
	v_pk_fma_f32 v[12:13], v[10:11], v[2:3], v[12:13] op_sel_hi:[0,1,1]
	v_pk_fma_f32 v[12:13], v[18:19], v[24:25], v[12:13] op_sel_hi:[0,1,1]
	v_rcp_f32_e32 v23, v7
	v_mul_f32_e32 v7, 0xbfb8aa3b, v12
	v_exp_f32_e32 v7, v7
	v_mul_f32_e32 v11, 0xbfb8aa3b, v13
	v_exp_f32_e32 v11, v11
	v_and_b32_e32 v5, 0xffff0000, v35
	v_pk_fma_f32 v[2:3], v[122:123], v[2:3], v[6:7] op_sel_hi:[0,1,0]
	v_pk_fma_f32 v[2:3], v[124:125], v[24:25], v[2:3] op_sel_hi:[0,1,1]
	v_mov_b32_e32 v4, v1
	v_pk_fma_f32 v[2:3], v[10:11], v[0:1], v[2:3] op_sel_hi:[0,1,1]
	v_add_f32_e32 v7, 1.0, v7
	v_pk_fma_f32 v[2:3], v[18:19], v[4:5], v[2:3] op_sel_hi:[0,1,1]
	v_rcp_f32_e32 v20, v7
	v_add_f32_e32 v7, 1.0, v11
	v_mul_f32_e32 v11, 0xbfb8aa3b, v2
	v_exp_f32_e32 v11, v11
	v_mul_f32_e32 v19, 0xbfb8aa3b, v3
	v_exp_f32_e32 v19, v19
	v_rcp_f32_e32 v21, v7
	v_add_f32_e32 v7, 1.0, v11
	v_rcp_f32_e32 v24, v7
	v_add_f32_e32 v7, 1.0, v19
	v_pk_fma_f32 v[0:1], v[122:123], v[0:1], v[6:7] op_sel_hi:[0,1,0]
	v_and_b32_e32 v9, 0xffff0000, v47
	v_mov_b32_e32 v8, v5
	v_pk_fma_f32 v[0:1], v[124:125], v[4:5], v[0:1] op_sel_hi:[0,1,1]
	v_and_b32_e32 v15, 0xffff0000, v39
	v_mov_b32_e32 v14, v9
	v_pk_fma_f32 v[0:1], v[10:11], v[8:9], v[0:1] op_sel_hi:[0,1,1]
	v_pk_fma_f32 v[0:1], v[18:19], v[14:15], v[0:1] op_sel_hi:[0,1,1]
	v_mul_f32_e32 v4, 0xbfb8aa3b, v0
	v_mul_f32_e32 v5, 0xbfb8aa3b, v1
	v_exp_f32_e32 v4, v4
	v_exp_f32_e32 v5, v5
	v_rcp_f32_e32 v25, v7
	v_pk_mul_f32 v[62:63], v[106:107], v[162:163]
	v_add_f32_e32 v4, 1.0, v4
	v_add_f32_e32 v5, 1.0, v5
	v_rcp_f32_e32 v4, v4
	v_rcp_f32_e32 v5, v5
	v_pk_mul_f32 v[66:67], v[158:159], v[164:165]
	v_pk_mul_f32 v[106:107], v[148:149], v[152:153]
	v_pk_mul_f32 v[130:131], v[130:131], v[140:141]
	v_pk_mul_f32 v[34:35], v[16:17], v[22:23]
	v_pk_mul_f32 v[38:39], v[12:13], v[20:21]
	v_pk_mul_f32 v[42:43], v[2:3], v[24:25]
	v_pk_mul_f32 v[46:47], v[0:1], v[4:5]
	s_and_saveexec_b64 s[28:29], vcc
	s_xor_b64 s[28:29], exec, s[28:29]
	s_cbranch_execz .LBB0_275
; __device__ __forceinline__ u32x4 pack8(const float* f) { u32x4 o; o.x = pk2(f[0], f[1]); o.y = pk2(f[2], f[3]); o.z = pk2(f[4], f[5]); o.w = pk2(f[6], f[7]); return o; }
; __device__ __forceinline__ float silu_f(float x) { return x * __builtin_amdgcn_rcpf(1.0f + __expf(-x)); }
; __device__ __forceinline__ void phase_layout(const PT& p, int tid) {
;     ...
;             for (int i = 0; i < 8; ++i)
; #pragma unroll
;                 for (int j = 0; j < 8; ++j) { float a = cb[j];
; #pragma unroll
;                     for (int kk = 0; kk < 4; ++kk) a += cw[kk][j] * xw[i + kk][j];
;                     o[i][j] = silu_f(a); }
;             if (k < 32) {
; #pragma unroll
;                 for (int j = 0; j < 8; ++j) { float c8[8];
; #pragma unroll
;                     for (int i = 0; i < 8; ++i) c8[i] = o[i][j];
;                     *(u32x4*)(xT + ((size_t)bc * 2048 + sc0 + j) * 128 + so * 8) = pack8(c8); }
;             } else if (k < 36) {
;                 const int n0 = sc0 - 2048;
; #pragma unroll
;                 for (int i = 0; i < 8; ++i) *(u32x4*)(Bn + (size_t)(tok0 + i) * 512 + n0) = pack8(o[i]);
; #pragma unroll
;                 for (int j = 0; j < 8; ++j) { float c8[8];
; #pragma unroll
;                     for (int i = 0; i < 8; ++i) c8[i] = o[i][j];
;                     *(u32x4*)(BT + ((size_t)bc * 512 + n0 + j) * 128 + so * 8) = pack8(c8); }
;             } else {
;                 const int n0 = sc0 - 2560;
; #pragma unroll
;                 for (int i = 0; i < 8; ++i) *(u32x4*)(Cn + (size_t)(tok0 + i) * 512 + n0) = pack8(o[i]);
;             }
	v_ashrrev_i32_e32 v85, 31, v84
	v_ashrrev_i32_e32 v111, 31, v110
	v_ashrrev_i32_e32 v113, 31, v112
	v_ashrrev_i32_e32 v115, 31, v114
	v_cmp_lt_u32_e32 vcc, 19, v88
	v_lshlrev_b64 v[116:117], 10, v[84:85]
	v_lshlrev_b64 v[108:109], 10, v[110:111]
	v_lshlrev_b64 v[88:89], 10, v[112:113]
	v_lshlrev_b64 v[84:85], 10, v[114:115]
	v_cvt_pk_bf16_f32 v28, v90, v48
	v_cvt_pk_bf16_f32 v29, v62, v32
	v_cvt_pk_bf16_f32 v30, v50, v128
	v_cvt_pk_bf16_f32 v31, v118, v34
	v_cvt_pk_bf16_f32 v24, v91, v49
	v_cvt_pk_bf16_f32 v25, v63, v33
	v_cvt_pk_bf16_f32 v26, v51, v129
	v_cvt_pk_bf16_f32 v27, v119, v35
	v_cvt_pk_bf16_f32 v20, v92, v52
	v_cvt_pk_bf16_f32 v21, v64, v36
	v_cvt_pk_bf16_f32 v22, v54, v130
	v_cvt_pk_bf16_f32 v23, v126, v38
	v_cvt_pk_bf16_f32 v16, v93, v53
	v_cvt_pk_bf16_f32 v17, v65, v37
	v_cvt_pk_bf16_f32 v18, v55, v131
	v_cvt_pk_bf16_f32 v19, v127, v39
	v_cvt_pk_bf16_f32 v12, v94, v56
	v_cvt_pk_bf16_f32 v13, v66, v40
	v_cvt_pk_bf16_f32 v14, v58, v132
	v_cvt_pk_bf16_f32 v15, v136, v42
	v_cvt_pk_bf16_f32 v8, v95, v57
	v_cvt_pk_bf16_f32 v9, v67, v41
	v_cvt_pk_bf16_f32 v10, v59, v133
	v_cvt_pk_bf16_f32 v11, v137, v43
	v_cvt_pk_bf16_f32 v4, v96, v60
	v_cvt_pk_bf16_f32 v5, v106, v44
	v_cvt_pk_bf16_f32 v6, v120, v134
	v_cvt_pk_bf16_f32 v7, v138, v46
	v_cvt_pk_bf16_f32 v0, v97, v61
	v_cvt_pk_bf16_f32 v1, v107, v45
	v_cvt_pk_bf16_f32 v2, v121, v135
	v_cvt_pk_bf16_f32 v3, v139, v47
	s_and_saveexec_b64 s[30:31], vcc
	s_xor_b64 s[30:31], exec, s[30:31]
	s_cbranch_execz .LBB0_272
	v_lshl_add_u64 v[32:33], v[70:71], 1, s[4:5]
	v_lshl_add_u64 v[34:35], v[32:33], 0, v[116:117]
	v_add_co_u32_e32 v34, vcc, s38, v34
	v_ashrrev_i32_e32 v105, 31, v104
	s_nop 0
	v_addc_co_u32_e32 v35, vcc, 0, v35, vcc
	global_store_dwordx4 v[34:35], v[28:31], off offset:3072
	v_ashrrev_i32_e32 v103, 31, v102
	v_ashrrev_i32_e32 v101, 31, v100
	v_lshl_add_u64 v[28:29], v[32:33], 0, v[108:109]
	v_add_co_u32_e32 v28, vcc, s38, v28
	v_ashrrev_i32_e32 v99, 31, v98
	s_nop 0
	v_addc_co_u32_e32 v29, vcc, 0, v29, vcc
	global_store_dwordx4 v[28:29], v[24:27], off offset:3072
	s_nop 1
	v_lshl_add_u64 v[24:25], v[32:33], 0, v[88:89]
	v_add_co_u32_e32 v24, vcc, s38, v24
	s_nop 1
	v_addc_co_u32_e32 v25, vcc, 0, v25, vcc
	global_store_dwordx4 v[24:25], v[20:23], off offset:3072
	s_nop 1
	v_lshl_add_u64 v[20:21], v[32:33], 0, v[84:85]
	v_add_co_u32_e32 v20, vcc, s38, v20
	s_nop 1
	v_addc_co_u32_e32 v21, vcc, 0, v21, vcc
	global_store_dwordx4 v[20:21], v[16:19], off offset:3072
	s_nop 1
	v_lshlrev_b64 v[16:17], 10, v[104:105]
	v_lshl_add_u64 v[16:17], v[32:33], 0, v[16:17]
	v_add_co_u32_e32 v16, vcc, s38, v16
	s_nop 1
	v_addc_co_u32_e32 v17, vcc, 0, v17, vcc
	global_store_dwordx4 v[16:17], v[12:15], off offset:3072
	s_nop 1
	v_lshlrev_b64 v[12:13], 10, v[102:103]
	v_lshl_add_u64 v[12:13], v[32:33], 0, v[12:13]
	v_add_co_u32_e32 v12, vcc, s38, v12
	s_nop 1
	v_addc_co_u32_e32 v13, vcc, 0, v13, vcc
	global_store_dwordx4 v[12:13], v[8:11], off offset:3072
	s_nop 1
	v_lshlrev_b64 v[8:9], 10, v[100:101]
	v_lshl_add_u64 v[8:9], v[32:33], 0, v[8:9]
	v_add_co_u32_e32 v8, vcc, s38, v8
	s_nop 1
	v_addc_co_u32_e32 v9, vcc, 0, v9, vcc
	global_store_dwordx4 v[8:9], v[4:7], off offset:3072
	s_nop 1
	v_lshlrev_b64 v[4:5], 10, v[98:99]
	v_lshl_add_u64 v[4:5], v[32:33], 0, v[4:5]
	v_add_co_u32_e32 v4, vcc, 0x1e8fe000, v4
	s_nop 1
	v_addc_co_u32_e32 v5, vcc, 0, v5, vcc
	global_store_dwordx4 v[4:5], v[0:3], off offset:3072

; __device__ __forceinline__ void unpack8(u32x4 r, float* f) { f[0] = bflo(r.x); f[1] = bfhi(r.x); f[2] = bflo(r.y); f[3] = bfhi(r.y); f[4] = bflo(r.z); f[5] = bfhi(r.z); f[6] = bflo(r.w); f[7] = bfhi(r.w); }
; __device__ __forceinline__ void phase_layout(const PT& p, int tid) {
;     ...
;             const int ch0 = k * 128 + co * 8;
;             float g[8], bb[8];
; #pragma unroll
;             for (int j = 0; j < 8; ++j) { g[j] = p.in[3][ch0 + j]; bb[j] = p.in[4][ch0 + j]; }
; #pragma unroll
;             for (int i = 0; i < 8; ++i) {
;                 const int row = tok0 + i; float f[8]; unpack8(*(const u32x4*)(Vb + (size_t)row * 2048 + ch0), f);
;                 const float mu = st0[2 * row] * (1.f / 2048.f), var = st0[2 * row + 1] * (1.f / 2048.f) - mu * mu, rs = rsqrtf(fmaxf(var, 0.f) + EPS);
; #pragma unroll
;                 for (int j = 0; j < 8; ++j) o[i][j] = (f[j] - mu) * rs * g[j] + bb[j];
;             }
.LBB0_278:
	s_andn2_saveexec_b64 s[28:29], s[0:1]
	s_cbranch_execz .LBB0_261
	ds_read_b64 v[6:7], v125
	ds_read_b64 v[12:13], v154
	v_lshlrev_b32_e32 v2, 1, v84
	v_mad_u64_u32 v[0:1], s[0:1], v82, s33, v[78:79]
	v_ashrrev_i32_e32 v3, 31, v2
	v_add_u32_e32 v8, -7, v0
	v_lshl_add_u64 v[2:3], v[2:3], 2, s[4:5]
	global_load_dwordx3 v[2:4], v[2:3], off
	v_ashrrev_i32_e32 v9, 31, v8
	v_or_b32_e32 v22, 1, v84
	s_waitcnt lgkmcnt(1)
	v_readfirstlane_b32 s1, v7
	v_readfirstlane_b32 s0, v6
	v_lshlrev_b64 v[6:7], 2, v[8:9]
	s_waitcnt lgkmcnt(0)
	v_readfirstlane_b32 s31, v13
	v_lshlrev_b32_e32 v14, 1, v22
	v_readfirstlane_b32 s30, v12
	v_lshl_add_u64 v[10:11], s[0:1], 0, v[6:7]
	v_ashrrev_i32_e32 v15, 31, v14
	v_lshl_add_u64 v[6:7], s[30:31], 0, v[6:7]
	v_lshl_add_u64 v[14:15], v[14:15], 2, s[4:5]
	global_load_dword v16, v[6:7], off
	v_add_u32_e32 v6, -6, v0
	global_load_dword v40, v[14:15], off offset:4
	v_ashrrev_i32_e32 v7, 31, v6
	v_lshlrev_b64 v[6:7], 2, v[6:7]
	v_lshl_add_u64 v[12:13], s[0:1], 0, v[6:7]
	v_lshl_add_u64 v[6:7], s[30:31], 0, v[6:7]
	global_load_dword v18, v[6:7], off
	v_add_u32_e32 v6, -5, v0
	v_ashrrev_i32_e32 v7, 31, v6
	v_lshlrev_b64 v[6:7], 2, v[6:7]
	v_lshl_add_u64 v[14:15], s[0:1], 0, v[6:7]
	v_lshl_add_u64 v[6:7], s[30:31], 0, v[6:7]
	global_load_dword v20, v[6:7], off
	v_add_u32_e32 v6, -4, v0
	v_ashrrev_i32_e32 v23, 31, v22
	v_lshl_add_u64 v[38:39], v[8:9], 1, s[8:9]
	v_ashrrev_i32_e32 v85, 31, v84
	v_lshlrev_b64 v[22:23], 12, v[22:23]
	v_ashrrev_i32_e32 v7, 31, v6
	v_lshlrev_b64 v[24:25], 12, v[84:85]
	v_lshl_add_u64 v[22:23], v[38:39], 0, v[22:23]
	v_lshlrev_b64 v[6:7], 2, v[6:7]
	global_load_dword v10, v[10:11], off
	v_lshl_add_u64 v[24:25], v[38:39], 0, v[24:25]
	global_load_dword v12, v[12:13], off
	v_ashrrev_i32_e32 v1, 31, v0
	global_load_dword v14, v[14:15], off
	s_nop 0
	global_load_dwordx4 v[58:61], v[22:23], off nt
	global_load_dwordx4 v[62:65], v[24:25], off nt
	v_lshl_add_u64 v[22:23], s[0:1], 0, v[6:7]
	v_lshl_add_u64 v[6:7], s[30:31], 0, v[6:7]
	global_load_dword v30, v[6:7], off
	v_add_u32_e32 v6, -3, v0
	v_ashrrev_i32_e32 v7, 31, v6
	v_lshlrev_b64 v[6:7], 2, v[6:7]
	v_lshl_add_u64 v[24:25], s[0:1], 0, v[6:7]
	v_lshl_add_u64 v[6:7], s[30:31], 0, v[6:7]
	global_load_dword v32, v[6:7], off
	v_add_u32_e32 v6, -2, v0
	v_ashrrev_i32_e32 v7, 31, v6
	v_lshlrev_b64 v[6:7], 2, v[6:7]
	v_lshl_add_u64 v[26:27], s[0:1], 0, v[6:7]
	v_lshl_add_u64 v[6:7], s[30:31], 0, v[6:7]
	global_load_dword v34, v[6:7], off
	v_add_u32_e32 v6, -1, v0
	v_ashrrev_i32_e32 v7, 31, v6
	v_lshlrev_b64 v[6:7], 2, v[6:7]
	v_lshl_add_u64 v[28:29], s[0:1], 0, v[6:7]
	v_lshl_add_u64 v[6:7], s[30:31], 0, v[6:7]
	global_load_dword v36, v[6:7], off
	v_or_b32_e32 v6, 2, v84
	v_lshlrev_b32_e32 v42, 1, v6
	global_load_dword v22, v[22:23], off
	v_ashrrev_i32_e32 v43, 31, v42
	v_lshl_add_u64 v[42:43], v[42:43], 2, s[4:5]
	global_load_dwordx2 v[66:67], v[42:43], off
	v_or_b32_e32 v42, 3, v84
	global_load_dword v24, v[24:25], off
	v_lshlrev_b32_e32 v44, 1, v42
	v_ashrrev_i32_e32 v45, 31, v44
	v_lshl_add_u64 v[44:45], v[44:45], 2, s[4:5]
	global_load_dword v26, v[26:27], off
	v_lshlrev_b64 v[0:1], 2, v[0:1]
	global_load_dwordx2 v[86:87], v[44:45], off
	v_lshl_add_u64 v[44:45], s[0:1], 0, v[0:1]
	global_load_dword v50, v[44:45], off
	v_lshl_add_u64 v[0:1], s[30:31], 0, v[0:1]
	s_waitcnt vmcnt(19)
	v_mov_b32_e32 v88, v2
	v_mov_b32_e32 v89, v4
	v_pk_mul_f32 v[4:5], v[88:89], s[22:23] op_sel_hi:[1,0]
	v_mov_b32_e32 v2, v3
	v_mov_b32_e32 v3, v4
	v_mov_b32_e32 v81, v4
	v_pk_mul_f32 v[2:3], v[2:3], v[80:81]
	v_mov_b32_e32 v41, v5
	v_mov_b32_e32 v81, v5
	v_sub_f32_e32 v2, v2, v3
	v_max_f32_e32 v2, 0, v2
	v_ashrrev_i32_e32 v7, 31, v6
	v_ashrrev_i32_e32 v43, 31, v42
	global_load_dword v52, v[0:1], off
	v_lshlrev_b64 v[0:1], 12, v[6:7]
	s_waitcnt vmcnt(18)
	v_pk_mul_f32 v[4:5], v[40:41], v[80:81]
	v_lshl_add_u64 v[0:1], v[38:39], 0, v[0:1]
	v_sub_f32_e32 v3, v4, v5
	v_max_f32_e32 v3, 0, v3
	v_pk_add_f32 v[2:3], v[2:3], s[24:25] op_sel_hi:[1,0]
	global_load_dword v28, v[28:29], off
	v_mul_f32_e32 v4, 0x4b800000, v2
	v_cmp_gt_f32_e32 vcc, s39, v2
	v_cmp_gt_f32_e64 s[0:1], s39, v3
	v_or_b32_e32 v92, 5, v84
	v_cndmask_b32_e32 v2, v2, v4, vcc
	v_rsq_f32_e32 v40, v2
	v_mul_f32_e32 v2, 0x4b800000, v3
	v_cndmask_b32_e64 v2, v3, v2, s[0:1]
	v_rsq_f32_e32 v41, v2
	v_lshlrev_b64 v[2:3], 12, v[42:43]
	v_lshl_add_u64 v[2:3], v[38:39], 0, v[2:3]
	global_load_dwordx4 v[4:7], v[2:3], off nt
	s_nop 0
	global_load_dwordx4 v[0:3], v[0:1], off nt
	v_pk_mul_f32 v[44:45], v[40:41], s[26:27] op_sel_hi:[1,0]
	v_ashrrev_i32_e32 v93, 31, v92
	v_cndmask_b32_e64 v91, v41, v45, s[0:1]
	v_cndmask_b32_e32 v90, v40, v44, vcc
	v_ashrrev_i32_e32 v83, 31, v82
	s_waitcnt vmcnt(15)
	v_lshlrev_b32_e32 v41, 16, v58
	s_waitcnt vmcnt(14)
	v_lshlrev_b32_e32 v40, 16, v62
	v_pk_fma_f32 v[40:41], v[88:89], s[22:23], v[40:41] op_sel_hi:[1,0,1] neg_lo:[1,0,0] neg_hi:[1,0,0]
	s_waitcnt vmcnt(1)
	v_lshlrev_b32_e32 v101, 16, v7
	v_pk_mul_f32 v[40:41], v[40:41], v[90:91]
	s_waitcnt vmcnt(0)
; __device__ __forceinline__ void unpack8(u32x4 r, float* f) { f[0] = bflo(r.x); f[1] = bfhi(r.x); f[2] = bflo(r.y); f[3] = bfhi(r.y); f[4] = bflo(r.z); f[5] = bfhi(r.z); f[6] = bflo(r.w); f[7] = bfhi(r.w); }
; __device__ __forceinline__ void phase_layout(const PT& p, int tid) {
;     ...
; #pragma unroll
;             for (int i = 0; i < 8; ++i) {
;                 const int row = tok0 + i; float f[8]; unpack8(*(const u32x4*)(Vb + (size_t)row * 2048 + ch0), f);
;                 const float mu = st0[2 * row] * (1.f / 2048.f), var = st0[2 * row + 1] * (1.f / 2048.f) - mu * mu, rs = rsqrtf(fmaxf(var, 0.f) + EPS);
; #pragma unroll
;                 for (int j = 0; j < 8; ++j) o[i][j] = (f[j] - mu) * rs * g[j] + bb[j];
;             }
	v_lshlrev_b32_e32 v100, 16, v3
	v_pk_fma_f32 v[56:57], v[10:11], v[40:41], v[16:17] op_sel_hi:[0,1,0]
	v_and_b32_e32 v41, 0xffff0000, v58
	v_and_b32_e32 v40, 0xffff0000, v62
	v_pk_fma_f32 v[40:41], v[88:89], s[22:23], v[40:41] op_sel_hi:[1,0,1] neg_lo:[1,0,0] neg_hi:[1,0,0]
	v_and_b32_e32 v58, 0xffff0000, v65
	v_pk_mul_f32 v[40:41], v[40:41], v[90:91]
	v_mov_b32_e32 v62, v67
	v_pk_fma_f32 v[54:55], v[12:13], v[40:41], v[18:19] op_sel_hi:[0,1,0]
	v_lshlrev_b32_e32 v41, 16, v59
	v_lshlrev_b32_e32 v40, 16, v63
	v_pk_fma_f32 v[40:41], v[88:89], s[22:23], v[40:41] op_sel_hi:[1,0,1] neg_lo:[1,0,0] neg_hi:[1,0,0]
	v_and_b32_e32 v110, 0xffff0000, v3
	v_pk_mul_f32 v[40:41], v[40:41], v[90:91]
	v_and_b32_e32 v111, 0xffff0000, v7
	v_pk_fma_f32 v[48:49], v[14:15], v[40:41], v[20:21] op_sel_hi:[0,1,0]
	v_and_b32_e32 v41, 0xffff0000, v59
	v_and_b32_e32 v40, 0xffff0000, v63
	v_pk_fma_f32 v[40:41], v[88:89], s[22:23], v[40:41] op_sel_hi:[1,0,1] neg_lo:[1,0,0] neg_hi:[1,0,0]
	v_and_b32_e32 v59, 0xffff0000, v61
	v_pk_mul_f32 v[40:41], v[40:41], v[90:91]
	v_pk_fma_f32 v[58:59], v[88:89], s[22:23], v[58:59] op_sel_hi:[1,0,1] neg_lo:[1,0,0] neg_hi:[1,0,0]
	v_pk_fma_f32 v[46:47], v[22:23], v[40:41], v[30:31] op_sel_hi:[0,1,0]
	v_lshlrev_b32_e32 v41, 16, v60
	v_lshlrev_b32_e32 v40, 16, v64
	v_pk_fma_f32 v[40:41], v[88:89], s[22:23], v[40:41] op_sel_hi:[1,0,1] neg_lo:[1,0,0] neg_hi:[1,0,0]
	v_pk_mul_f32 v[58:59], v[58:59], v[90:91]
	v_pk_mul_f32 v[40:41], v[40:41], v[90:91]
	v_pk_fma_f32 v[58:59], v[50:51], v[58:59], v[52:53] op_sel_hi:[0,1,0]
	v_pk_fma_f32 v[44:45], v[24:25], v[40:41], v[32:33] op_sel_hi:[0,1,0]
	v_and_b32_e32 v41, 0xffff0000, v60
	v_and_b32_e32 v40, 0xffff0000, v64
	v_pk_fma_f32 v[40:41], v[88:89], s[22:23], v[40:41] op_sel_hi:[1,0,1] neg_lo:[1,0,0] neg_hi:[1,0,0]
	v_mov_b32_e32 v64, v66
	v_pk_mul_f32 v[40:41], v[40:41], v[90:91]
	s_nop 0
	v_pk_fma_f32 v[42:43], v[26:27], v[40:41], v[34:35] op_sel_hi:[0,1,0]
	v_lshlrev_b32_e32 v40, 16, v65
	v_mov_b32_e32 v65, v86
	v_or_b32_e32 v86, 4, v84
	v_lshlrev_b32_e32 v66, 1, v86
	v_ashrrev_i32_e32 v67, 31, v66
	v_lshl_add_u64 v[66:67], v[66:67], 2, s[4:5]
	global_load_dwordx2 v[96:97], v[66:67], off
	v_lshlrev_b32_e32 v66, 1, v92
	v_ashrrev_i32_e32 v67, 31, v66
	v_lshl_add_u64 v[66:67], v[66:67], 2, s[4:5]
	global_load_dwordx2 v[98:99], v[66:67], off
	v_lshlrev_b32_e32 v41, 16, v61
	v_pk_mul_f32 v[60:61], v[64:65], s[22:23] op_sel_hi:[1,0]
	v_pk_fma_f32 v[40:41], v[88:89], s[22:23], v[40:41] op_sel_hi:[1,0,1] neg_lo:[1,0,0] neg_hi:[1,0,0]
	v_mov_b32_e32 v63, v60
	v_mov_b32_e32 v81, v60
	v_pk_mul_f32 v[62:63], v[62:63], v[80:81]
	v_mov_b32_e32 v60, v87
	v_mov_b32_e32 v81, v61
	v_sub_f32_e32 v11, v62, v63
	v_pk_mul_f32 v[60:61], v[60:61], v[80:81]
	v_max_f32_e32 v62, 0, v11
	v_sub_f32_e32 v11, v60, v61
	v_max_f32_e32 v63, 0, v11
	v_pk_add_f32 v[60:61], v[62:63], s[24:25] op_sel_hi:[1,0]
	v_ashrrev_i32_e32 v87, 31, v86
	v_mul_f32_e32 v11, 0x4b800000, v60
	v_cmp_gt_f32_e32 vcc, s39, v60
	v_cmp_gt_f32_e64 s[0:1], s39, v61
	v_pk_mul_f32 v[40:41], v[40:41], v[90:91]
	v_cndmask_b32_e32 v11, v60, v11, vcc
	v_rsq_f32_e32 v60, v11
	v_mul_f32_e32 v11, 0x4b800000, v61
	v_cndmask_b32_e64 v11, v61, v11, s[0:1]
	v_rsq_f32_e32 v61, v11
	v_pk_fma_f32 v[100:101], v[64:65], s[22:23], v[100:101] op_sel_hi:[1,0,1] neg_lo:[1,0,0] neg_hi:[1,0,0]
	v_pk_fma_f32 v[40:41], v[28:29], v[40:41], v[36:37] op_sel_hi:[0,1,0]
	v_pk_mul_f32 v[62:63], v[60:61], s[26:27] op_sel_hi:[1,0]
	s_nop 0
	v_cndmask_b32_e64 v105, v61, v63, s[0:1]
	v_cndmask_b32_e32 v104, v60, v62, vcc
	v_lshlrev_b32_e32 v61, 16, v4
	v_lshlrev_b32_e32 v60, 16, v0
	v_pk_fma_f32 v[60:61], v[64:65], s[22:23], v[60:61] op_sel_hi:[1,0,1] neg_lo:[1,0,0] neg_hi:[1,0,0]
	v_lshlrev_b64 v[62:63], 12, v[86:87]
	v_pk_mul_f32 v[60:61], v[60:61], v[104:105]
	v_lshlrev_b64 v[86:87], 12, v[92:93]
	v_pk_fma_f32 v[66:67], v[10:11], v[60:61], v[16:17] op_sel_hi:[0,1,0]
	v_and_b32_e32 v61, 0xffff0000, v4
	v_and_b32_e32 v60, 0xffff0000, v0
	v_pk_fma_f32 v[60:61], v[64:65], s[22:23], v[60:61] op_sel_hi:[1,0,1] neg_lo:[1,0,0] neg_hi:[1,0,0]
	v_lshl_add_u64 v[86:87], v[38:39], 0, v[86:87]
	v_pk_mul_f32 v[60:61], v[60:61], v[104:105]
	v_lshl_add_u64 v[62:63], v[38:39], 0, v[62:63]
	global_load_dwordx4 v[88:91], v[86:87], off nt
	global_load_dwordx4 v[92:95], v[62:63], off nt
	v_pk_fma_f32 v[86:87], v[12:13], v[60:61], v[18:19] op_sel_hi:[0,1,0]
	v_lshlrev_b32_e32 v61, 16, v5
	v_lshlrev_b32_e32 v60, 16, v1
	v_and_b32_e32 v5, 0xffff0000, v5
	v_and_b32_e32 v4, 0xffff0000, v1
	v_pk_fma_f32 v[60:61], v[64:65], s[22:23], v[60:61] op_sel_hi:[1,0,1] neg_lo:[1,0,0] neg_hi:[1,0,0]
	v_pk_fma_f32 v[0:1], v[64:65], s[22:23], v[4:5] op_sel_hi:[1,0,1] neg_lo:[1,0,0] neg_hi:[1,0,0]
	v_pk_mul_f32 v[60:61], v[60:61], v[104:105]
	v_pk_mul_f32 v[0:1], v[0:1], v[104:105]
	v_pk_fma_f32 v[62:63], v[14:15], v[60:61], v[20:21] op_sel_hi:[0,1,0]
	v_pk_fma_f32 v[60:61], v[22:23], v[0:1], v[30:31] op_sel_hi:[0,1,0]
	v_lshlrev_b32_e32 v1, 16, v6
	v_lshlrev_b32_e32 v0, 16, v2
	v_pk_fma_f32 v[0:1], v[64:65], s[22:23], v[0:1] op_sel_hi:[1,0,1] neg_lo:[1,0,0] neg_hi:[1,0,0]
	s_waitcnt vmcnt(3)
	v_mov_b32_e32 v112, v96
	v_pk_mul_f32 v[0:1], v[0:1], v[104:105]
	v_mov_b32_e32 v96, v97
	v_pk_fma_f32 v[4:5], v[24:25], v[0:1], v[32:33] op_sel_hi:[0,1,0]
	v_and_b32_e32 v1, 0xffff0000, v6
	v_and_b32_e32 v0, 0xffff0000, v2
	v_or_b32_e32 v2, 6, v84
	v_or_b32_e32 v6, 7, v84
	v_lshlrev_b32_e32 v102, 1, v2
	v_lshlrev_b32_e32 v84, 1, v6
	v_ashrrev_i32_e32 v103, 31, v102
	v_ashrrev_i32_e32 v85, 31, v84
	v_lshl_add_u64 v[102:103], v[102:103], 2, s[4:5]
	v_lshl_add_u64 v[84:85], v[84:85], 2, s[4:5]
	global_load_dwordx2 v[106:107], v[102:103], off
	global_load_dwordx2 v[108:109], v[84:85], off
	s_waitcnt vmcnt(4)
; __device__ __forceinline__ void unpack8(u32x4 r, float* f) { f[0] = bflo(r.x); f[1] = bfhi(r.x); f[2] = bflo(r.y); f[3] = bfhi(r.y); f[4] = bflo(r.z); f[5] = bfhi(r.z); f[6] = bflo(r.w); f[7] = bfhi(r.w); }
; __device__ __forceinline__ void phase_layout(const PT& p, int tid) {
;     ...
; #pragma unroll
;             for (int i = 0; i < 8; ++i) {
;                 const int row = tok0 + i; float f[8]; unpack8(*(const u32x4*)(Vb + (size_t)row * 2048 + ch0), f);
;                 const float mu = st0[2 * row] * (1.f / 2048.f), var = st0[2 * row + 1] * (1.f / 2048.f) - mu * mu, rs = rsqrtf(fmaxf(var, 0.f) + EPS);
; #pragma unroll
;                 for (int j = 0; j < 8; ++j) o[i][j] = (f[j] - mu) * rs * g[j] + bb[j];
;             }
	v_mov_b32_e32 v113, v98
	v_pk_mul_f32 v[84:85], v[100:101], v[104:105]
	v_pk_mul_f32 v[100:101], v[112:113], s[22:23] op_sel_hi:[1,0]
	v_ashrrev_i32_e32 v7, 31, v6
	v_mov_b32_e32 v97, v100
	v_mov_b32_e32 v81, v100
	v_pk_mul_f32 v[96:97], v[96:97], v[80:81]
	v_mov_b32_e32 v100, v99
	v_mov_b32_e32 v81, v101
	v_sub_f32_e32 v3, v96, v97
	v_pk_mul_f32 v[98:99], v[100:101], v[80:81]
	v_max_f32_e32 v96, 0, v3
	v_sub_f32_e32 v3, v98, v99
	v_max_f32_e32 v97, 0, v3
	v_ashrrev_i32_e32 v3, 31, v2
	v_lshlrev_b64 v[2:3], 12, v[2:3]
	v_lshl_add_u64 v[2:3], v[38:39], 0, v[2:3]
	v_pk_add_f32 v[114:115], v[96:97], s[24:25] op_sel_hi:[1,0]
	global_load_dwordx4 v[96:99], v[2:3], off nt
	v_lshlrev_b64 v[2:3], 12, v[6:7]
	v_lshl_add_u64 v[2:3], v[38:39], 0, v[2:3]
	global_load_dwordx4 v[100:103], v[2:3], off nt
	v_mul_f32_e32 v11, 0x4b800000, v114
	v_cmp_gt_f32_e32 vcc, s39, v114
	v_mul_f32_e32 v3, 0x4b800000, v115
	v_cmp_gt_f32_e64 s[0:1], s39, v115
	v_cndmask_b32_e32 v2, v114, v11, vcc
	v_rsq_f32_e32 v2, v2
	v_cndmask_b32_e64 v3, v115, v3, s[0:1]
	v_rsq_f32_e32 v3, v3
	v_pk_fma_f32 v[6:7], v[64:65], s[22:23], v[110:111] op_sel_hi:[1,0,1] neg_lo:[1,0,0] neg_hi:[1,0,0]
	v_pk_fma_f32 v[0:1], v[64:65], s[22:23], v[0:1] op_sel_hi:[1,0,1] neg_lo:[1,0,0] neg_hi:[1,0,0]
	v_pk_mul_f32 v[6:7], v[6:7], v[104:105]
	v_pk_mul_f32 v[0:1], v[0:1], v[104:105]
	v_pk_fma_f32 v[38:39], v[50:51], v[6:7], v[52:53] op_sel_hi:[0,1,0]
	v_pk_mul_f32 v[6:7], v[2:3], s[26:27] op_sel_hi:[1,0]
	s_waitcnt vmcnt(5)
	v_and_b32_e32 v65, 0xffff0000, v88
	v_cndmask_b32_e64 v3, v3, v7, s[0:1]
	v_cndmask_b32_e32 v2, v2, v6, vcc
	v_lshlrev_b32_e32 v7, 16, v88
	s_waitcnt vmcnt(4)
	v_lshlrev_b32_e32 v6, 16, v92
	v_and_b32_e32 v64, 0xffff0000, v92
	v_lshlrev_b32_e32 v104, 16, v93
	v_and_b32_e32 v88, 0xffff0000, v93
	v_lshlrev_b32_e32 v93, 16, v90
	v_lshlrev_b32_e32 v92, 16, v94
	v_and_b32_e32 v111, 0xffff0000, v90
	v_and_b32_e32 v110, 0xffff0000, v94
	v_lshlrev_b32_e32 v114, 16, v95
	v_and_b32_e32 v90, 0xffff0000, v95
	v_pk_fma_f32 v[6:7], v[112:113], s[22:23], v[6:7] op_sel_hi:[1,0,1] neg_lo:[1,0,0] neg_hi:[1,0,0]
	v_lshlrev_b32_e32 v105, 16, v89
	v_pk_mul_f32 v[6:7], v[6:7], v[2:3]
	v_and_b32_e32 v89, 0xffff0000, v89
	v_pk_fma_f32 v[6:7], v[10:11], v[6:7], v[16:17] op_sel_hi:[0,1,0]
	v_lshlrev_b32_e32 v115, 16, v91
	v_and_b32_e32 v91, 0xffff0000, v91
	v_pk_fma_f32 v[64:65], v[112:113], s[22:23], v[64:65] op_sel_hi:[1,0,1] neg_lo:[1,0,0] neg_hi:[1,0,0]
	v_pk_fma_f32 v[104:105], v[112:113], s[22:23], v[104:105] op_sel_hi:[1,0,1] neg_lo:[1,0,0] neg_hi:[1,0,0]
	v_pk_fma_f32 v[88:89], v[112:113], s[22:23], v[88:89] op_sel_hi:[1,0,1] neg_lo:[1,0,0] neg_hi:[1,0,0]
	v_pk_fma_f32 v[92:93], v[112:113], s[22:23], v[92:93] op_sel_hi:[1,0,1] neg_lo:[1,0,0] neg_hi:[1,0,0]
	v_pk_fma_f32 v[110:111], v[112:113], s[22:23], v[110:111] op_sel_hi:[1,0,1] neg_lo:[1,0,0] neg_hi:[1,0,0]
	v_pk_fma_f32 v[114:115], v[112:113], s[22:23], v[114:115] op_sel_hi:[1,0,1] neg_lo:[1,0,0] neg_hi:[1,0,0]
	v_pk_fma_f32 v[90:91], v[112:113], s[22:23], v[90:91] op_sel_hi:[1,0,1] neg_lo:[1,0,0] neg_hi:[1,0,0]
	v_pk_mul_f32 v[64:65], v[64:65], v[2:3]
	v_pk_mul_f32 v[104:105], v[104:105], v[2:3]
	v_pk_mul_f32 v[88:89], v[88:89], v[2:3]
	v_pk_mul_f32 v[92:93], v[92:93], v[2:3]
	v_pk_mul_f32 v[110:111], v[110:111], v[2:3]
	v_pk_mul_f32 v[114:115], v[114:115], v[2:3]
	v_pk_mul_f32 v[2:3], v[90:91], v[2:3]
	v_pk_fma_f32 v[64:65], v[12:13], v[64:65], v[18:19] op_sel_hi:[0,1,0]
	v_pk_fma_f32 v[90:91], v[50:51], v[2:3], v[52:53] op_sel_hi:[0,1,0]
	v_pk_fma_f32 v[104:105], v[14:15], v[104:105], v[20:21] op_sel_hi:[0,1,0]
	v_pk_fma_f32 v[88:89], v[22:23], v[88:89], v[30:31] op_sel_hi:[0,1,0]
	v_pk_fma_f32 v[92:93], v[24:25], v[92:93], v[32:33] op_sel_hi:[0,1,0]
	v_pk_fma_f32 v[0:1], v[26:27], v[0:1], v[34:35] op_sel_hi:[0,1,0]
	v_pk_fma_f32 v[110:111], v[26:27], v[110:111], v[34:35] op_sel_hi:[0,1,0]
	s_waitcnt vmcnt(3)
	v_mov_b32_e32 v94, v106
	s_waitcnt vmcnt(2)
	v_mov_b32_e32 v95, v108
	v_pk_mul_f32 v[116:117], v[94:95], s[22:23] op_sel_hi:[1,0]
	v_mov_b32_e32 v106, v107
	v_mov_b32_e32 v107, v116
	v_mov_b32_e32 v81, v116
	v_pk_mul_f32 v[106:107], v[106:107], v[80:81]
	v_mov_b32_e32 v116, v109
	v_mov_b32_e32 v81, v117
	v_sub_f32_e32 v11, v106, v107
	v_pk_mul_f32 v[108:109], v[116:117], v[80:81]
	v_max_f32_e32 v106, 0, v11
	v_sub_f32_e32 v11, v108, v109
	v_max_f32_e32 v107, 0, v11
	v_pk_add_f32 v[106:107], v[106:107], s[24:25] op_sel_hi:[1,0]
	v_pk_fma_f32 v[84:85], v[28:29], v[84:85], v[36:37] op_sel_hi:[0,1,0]
	v_mul_f32_e32 v11, 0x4b800000, v106
	v_cmp_gt_f32_e32 vcc, s39, v106
	v_cmp_gt_f32_e64 s[0:1], s39, v107
	v_pk_fma_f32 v[114:115], v[28:29], v[114:115], v[36:37] op_sel_hi:[0,1,0]
	v_cndmask_b32_e32 v11, v106, v11, vcc
	v_rsq_f32_e32 v106, v11
	v_mul_f32_e32 v11, 0x4b800000, v107
	v_cndmask_b32_e64 v11, v107, v11, s[0:1]
	v_rsq_f32_e32 v107, v11
	s_nop 0
	v_pk_mul_f32 v[2:3], v[106:107], s[26:27] op_sel_hi:[1,0]
	s_nop 0
	v_cndmask_b32_e64 v3, v107, v3, s[0:1]
	v_cndmask_b32_e32 v2, v106, v2, vcc
	s_waitcnt vmcnt(0)
; __device__ __forceinline__ u32x4 pack8(const float* f) { u32x4 o; o.x = pk2(f[0], f[1]); o.y = pk2(f[2], f[3]); o.z = pk2(f[4], f[5]); o.w = pk2(f[6], f[7]); return o; }
; __device__ __forceinline__ void phase_layout(const PT& p, int tid) {
;     ...
; #pragma unroll
;                 for (int j = 0; j < 8; ++j) o[i][j] = (f[j] - mu) * rs * g[j] + bb[j];
;             }
; #pragma unroll
;             for (int j = 0; j < 8; ++j) { float c8[8];
; #pragma unroll
;                 for (int i = 0; i < 8; ++i) c8[i] = o[i][j];
;                 *(u32x4*)(vT + ((size_t)bc * 2048 + ch0 + j) * 128 + so * 8) = pack8(c8); }
	v_lshlrev_b32_e32 v107, 16, v100
	v_lshlrev_b32_e32 v106, 16, v96
	v_pk_fma_f32 v[106:107], v[94:95], s[22:23], v[106:107] op_sel_hi:[1,0,1] neg_lo:[1,0,0] neg_hi:[1,0,0]
	s_nop 0
	v_pk_mul_f32 v[106:107], v[106:107], v[2:3]
	s_nop 0
	v_pk_fma_f32 v[16:17], v[10:11], v[106:107], v[16:17] op_sel_hi:[0,1,0]
	v_and_b32_e32 v11, 0xffff0000, v100
	v_and_b32_e32 v10, 0xffff0000, v96
	v_pk_fma_f32 v[10:11], v[94:95], s[22:23], v[10:11] op_sel_hi:[1,0,1] neg_lo:[1,0,0] neg_hi:[1,0,0]
	s_nop 0
	v_pk_mul_f32 v[10:11], v[10:11], v[2:3]
	s_nop 0
	v_pk_fma_f32 v[18:19], v[12:13], v[10:11], v[18:19] op_sel_hi:[0,1,0]
	v_lshlrev_b32_e32 v11, 16, v101
	v_lshlrev_b32_e32 v10, 16, v97
	v_pk_fma_f32 v[10:11], v[94:95], s[22:23], v[10:11] op_sel_hi:[1,0,1] neg_lo:[1,0,0] neg_hi:[1,0,0]
	v_cvt_pk_bf16_f32 v12, v6, v7
	v_pk_mul_f32 v[10:11], v[10:11], v[2:3]
	v_lshlrev_b64 v[6:7], 8, v[8:9]
	v_pk_fma_f32 v[14:15], v[14:15], v[10:11], v[20:21] op_sel_hi:[0,1,0]
	v_and_b32_e32 v11, 0xffff0000, v101
	v_and_b32_e32 v10, 0xffff0000, v97
	v_pk_fma_f32 v[10:11], v[94:95], s[22:23], v[10:11] op_sel_hi:[1,0,1] neg_lo:[1,0,0] neg_hi:[1,0,0]
	v_cvt_pk_bf16_f32 v13, v16, v17
	v_pk_mul_f32 v[10:11], v[10:11], v[2:3]
	v_cvt_pk_bf16_f32 v8, v64, v65
	v_pk_fma_f32 v[20:21], v[22:23], v[10:11], v[30:31] op_sel_hi:[0,1,0]
	v_lshlrev_b32_e32 v11, 16, v102
	v_lshlrev_b32_e32 v10, 16, v98
	v_pk_fma_f32 v[10:11], v[94:95], s[22:23], v[10:11] op_sel_hi:[1,0,1] neg_lo:[1,0,0] neg_hi:[1,0,0]
	v_cvt_pk_bf16_f32 v9, v18, v19
	v_pk_mul_f32 v[10:11], v[10:11], v[2:3]
	s_nop 0
	v_pk_fma_f32 v[22:23], v[24:25], v[10:11], v[32:33] op_sel_hi:[0,1,0]
	v_and_b32_e32 v11, 0xffff0000, v102
	v_and_b32_e32 v10, 0xffff0000, v98
	v_pk_fma_f32 v[10:11], v[94:95], s[22:23], v[10:11] op_sel_hi:[1,0,1] neg_lo:[1,0,0] neg_hi:[1,0,0]
	s_nop 0
	v_pk_mul_f32 v[10:11], v[10:11], v[2:3]
	s_nop 0
	v_pk_fma_f32 v[24:25], v[26:27], v[10:11], v[34:35] op_sel_hi:[0,1,0]
	v_lshlrev_b32_e32 v11, 16, v103
	v_lshlrev_b32_e32 v10, 16, v99
	v_pk_fma_f32 v[10:11], v[94:95], s[22:23], v[10:11] op_sel_hi:[1,0,1] neg_lo:[1,0,0] neg_hi:[1,0,0]
	s_nop 0
	v_pk_mul_f32 v[10:11], v[10:11], v[2:3]
	s_nop 0
	v_pk_fma_f32 v[26:27], v[28:29], v[10:11], v[36:37] op_sel_hi:[0,1,0]
	v_and_b32_e32 v11, 0xffff0000, v103
	v_and_b32_e32 v10, 0xffff0000, v99
	v_pk_fma_f32 v[10:11], v[94:95], s[22:23], v[10:11] op_sel_hi:[1,0,1] neg_lo:[1,0,0] neg_hi:[1,0,0]
	s_nop 0
	v_pk_mul_f32 v[2:3], v[10:11], v[2:3]
	v_cvt_pk_bf16_f32 v10, v56, v57
	v_pk_fma_f32 v[28:29], v[50:51], v[2:3], v[52:53] op_sel_hi:[0,1,0]
	v_lshlrev_b64 v[2:3], 19, v[82:83]
	v_lshl_add_u64 v[16:17], v[6:7], 0, v[2:3]
	v_cvt_pk_bf16_f32 v11, v66, v67
	v_lshl_add_u64 v[2:3], v[76:77], 0, v[16:17]
	global_store_dwordx4 v[2:3], v[10:13], off
	v_or_b32_e32 v2, 0x100, v16
	v_mov_b32_e32 v3, v17
	v_cvt_pk_bf16_f32 v6, v54, v55
	v_cvt_pk_bf16_f32 v7, v86, v87
	v_lshl_add_u64 v[2:3], v[76:77], 0, v[2:3]
	global_store_dwordx4 v[2:3], v[6:9], off
	v_or_b32_e32 v2, 0x200, v16
	v_mov_b32_e32 v3, v17
	v_cvt_pk_bf16_f32 v6, v48, v49
	v_cvt_pk_bf16_f32 v7, v62, v63
	v_cvt_pk_bf16_f32 v8, v104, v105
	v_cvt_pk_bf16_f32 v9, v14, v15
	v_lshl_add_u64 v[2:3], v[76:77], 0, v[2:3]
	global_store_dwordx4 v[2:3], v[6:9], off
	v_or_b32_e32 v2, 0x300, v16
	v_mov_b32_e32 v3, v17
	v_cvt_pk_bf16_f32 v6, v46, v47
	v_cvt_pk_bf16_f32 v7, v60, v61
	v_cvt_pk_bf16_f32 v8, v88, v89
	v_cvt_pk_bf16_f32 v9, v20, v21
	v_lshl_add_u64 v[2:3], v[76:77], 0, v[2:3]
	global_store_dwordx4 v[2:3], v[6:9], off
	v_cvt_pk_bf16_f32 v2, v44, v45
	v_cvt_pk_bf16_f32 v3, v4, v5
	v_or_b32_e32 v6, 0x400, v16
	v_mov_b32_e32 v7, v17
	v_cvt_pk_bf16_f32 v4, v92, v93
	v_cvt_pk_bf16_f32 v5, v22, v23
	v_lshl_add_u64 v[6:7], v[76:77], 0, v[6:7]
	global_store_dwordx4 v[6:7], v[2:5], off
	s_nop 1
	v_cvt_pk_bf16_f32 v3, v0, v1
	v_or_b32_e32 v0, 0x500, v16
	v_mov_b32_e32 v1, v17
	v_cvt_pk_bf16_f32 v2, v42, v43
	v_cvt_pk_bf16_f32 v4, v110, v111
	v_cvt_pk_bf16_f32 v5, v24, v25
	v_lshl_add_u64 v[0:1], v[76:77], 0, v[0:1]
	global_store_dwordx4 v[0:1], v[2:5], off
	v_cvt_pk_bf16_f32 v0, v40, v41
	v_cvt_pk_bf16_f32 v1, v84, v85
	v_or_b32_e32 v4, 0x600, v16
	v_mov_b32_e32 v5, v17
	v_cvt_pk_bf16_f32 v2, v114, v115
	v_cvt_pk_bf16_f32 v3, v26, v27
	v_lshl_add_u64 v[4:5], v[76:77], 0, v[4:5]
	v_or_b32_e32 v16, 0x700, v16
	global_store_dwordx4 v[4:5], v[0:3], off
	v_lshl_add_u64 v[4:5], v[76:77], 0, v[16:17]
	s_nop 0
	v_cvt_pk_bf16_f32 v0, v58, v59
	v_cvt_pk_bf16_f32 v1, v38, v39
	v_cvt_pk_bf16_f32 v2, v90, v91
	v_cvt_pk_bf16_f32 v3, v28, v29
	global_store_dwordx4 v[4:5], v[0:3], off
	s_branch .LBB0_261
